# phase 3 long scan: each step's MFMAs issued a1..a4 then b1..b4 with the later C operands unpacked into free registers (no dependent back-to-back pairs, hazard nops gone)
# baseline (speedup 1.0000x reference)
; DI unsigned pack2(float lo, float hi) { f32x2_t v = {lo, hi}; bf16x2_t b = __builtin_convertvector(v, bf16x2_t); return __builtin_bit_cast(unsigned, b); }
; DI float bflo(unsigned u) { return __uint_as_float(u << 16); }
; DI float bfhi(unsigned u) { return __uint_as_float(u & 0xffff0000u); }
; #define PINM do { asm volatile("" ::: "memory"); __builtin_amdgcn_sched_barrier(0); } while (0)
; DI void scan_step(const ScanSlot& s, f32x4 (&acc)[4], u16* sst, int irow, int g) {
;     unsigned pk[4][2];
; #pragma unroll
;     for (int mt = 0; mt < 4; ++mt) { pk[mt][0] = pack2(acc[mt][0], acc[mt][1]); pk[mt][1] = pack2(acc[mt][2], acc[mt][3]); }
;     bf16x8 bfr[2];
; #pragma unroll
;     for (int ks = 0; ks < 2; ++ks) { uint4 w = {pk[2 * ks][0], pk[2 * ks][1], pk[2 * ks + 1][0], pk[2 * ks + 1][1]}; bfr[ks] = __builtin_bit_cast(bf16x8, w);
;         { typedef unsigned u32x4_ __attribute__((ext_vector_type(4))); const u32x4_ wv_ = {w.x, w.y, w.z, w.w}; __builtin_nontemporal_store(wv_, (u32x4_*)(sst + irow * 64 + 32 * ks + 8 * g)); } }
; #pragma unroll
;     for (int mt = 0; mt < 4; ++mt) {
;         const unsigned hx = (mt & 1) ? s.gh[mt >> 1].z : s.gh[mt >> 1].x, hy = (mt & 1) ? s.gh[mt >> 1].w : s.gh[mt >> 1].y;
;         f32x4 c = {bflo(hx), bfhi(hx), bflo(hy), bfhi(hy)};
; #pragma unroll
;         for (int ks = 0; ks < 2; ++ks) c = __builtin_amdgcn_mfma_f32_16x16x32_bf16(__builtin_bit_cast(bf16x8, s.ga[mt][ks]), bfr[ks], c, 0, 0, 0);
;         acc[mt] = c;
;     }
; DI void scan_item(const Params& p, int item, int lane) {
;     ...
;             scan_step(s0, acc, SST + (size_t)u * 4096, irow, g);       PINM; scan_load(s0, GT, HH, min(u + 5, ul), irow, i16, g); PINM;
;             scan_step(s1, acc, SST + (size_t)(u + 1) * 4096, irow, g); PINM; scan_load(s1, GT, HH, min(u + 6, ul), irow, i16, g); PINM;
.Lscan_w0:
	s_waitcnt vmcnt(48)
	v_lshlrev_b32_e32 v214, 16, v110
	v_and_b32_e32 v215, 0xffff0000, v110
	v_lshlrev_b32_e32 v216, 16, v111
	v_and_b32_e32 v217, 0xffff0000, v111
	v_cvt_pk_bf16_f32 v202, v202, v203
	v_cvt_pk_bf16_f32 v203, v204, v205
	v_mfma_f32_16x16x32_bf16 v[106:109], v[106:109], v[206:209], v[214:217]
	v_lshlrev_b32_e32 v242, 16, v112
	v_and_b32_e32 v243, 0xffff0000, v112
	v_lshlrev_b32_e32 v244, 16, v113
	v_and_b32_e32 v245, 0xffff0000, v113
	v_lshlrev_b32_e32 v246, 16, v98
	v_and_b32_e32 v247, 0xffff0000, v98
	v_lshlrev_b32_e32 v248, 16, v99
	v_and_b32_e32 v249, 0xffff0000, v99
	v_lshlrev_b32_e32 v250, 16, v100
	v_and_b32_e32 v251, 0xffff0000, v100
	v_lshlrev_b32_e32 v252, 16, v101
	v_and_b32_e32 v253, 0xffff0000, v101
	v_cvt_pk_bf16_f32 v204, v210, v211
	v_cvt_pk_bf16_f32 v205, v212, v213
	s_nop 1
	v_mfma_f32_16x16x32_bf16 v[90:93], v[90:93], v[206:209], v[242:245]
	v_mfma_f32_16x16x32_bf16 v[82:85], v[82:85], v[206:209], v[246:249]
	v_mfma_f32_16x16x32_bf16 v[62:65], v[62:65], v[206:209], v[250:253]
	v_mfma_f32_16x16x32_bf16 v[210:213], v[102:105], v[202:205], v[106:109]
	v_mfma_f32_16x16x32_bf16 v[214:217], v[86:89], v[202:205], v[90:93]
	v_mfma_f32_16x16x32_bf16 v[232:235], v[78:81], v[202:205], v[82:85]
	v_add_co_u32_e32 v78, vcc, s7, v230
	s_nop 1
	v_addc_co_u32_e32 v79, vcc, -1, v231, vcc
	global_store_dwordx4 v[78:79], v[206:209], off offset:-64 nt
	global_store_dwordx4 v[78:79], v[202:205], off nt
	s_nop 1
	v_mfma_f32_16x16x32_bf16 v[202:205], v[50:53], v[202:205], v[62:65]
	s_add_i32 s14, s8, s6
	s_add_i32 s0, s14, 10
	s_min_u32 s0, s0, s10
	s_lshl_b32 s0, s0, 13
	v_lshl_add_u64 v[50:51], v[226:227], 0, s[0:1]
	global_load_dwordx4 v[106:109], v[50:51], off
	global_load_dwordx4 v[102:105], v[50:51], off offset:64
	global_load_dwordx4 v[90:93], v[50:51], off offset:2048
	global_load_dwordx4 v[86:89], v[50:51], off offset:2112
	v_add_co_u32_e32 v50, vcc, s9, v50
	v_lshl_add_u64 v[98:99], v[228:229], 0, s[0:1]
	s_nop 0
	v_addc_co_u32_e32 v51, vcc, 0, v51, vcc
	global_load_dwordx4 v[82:85], v[50:51], off
	global_load_dwordx4 v[78:81], v[50:51], off offset:64
	global_load_dwordx4 v[62:65], v[50:51], off offset:2048
	s_nop 0
	global_load_dwordx4 v[50:53], v[50:51], off offset:2112
	s_nop 0
	global_load_dwordx4 v[110:113], v[98:99], off
	s_nop 0
	global_load_dwordx4 v[98:101], v[98:99], off offset:64
	s_cmp_lg_u32 s6, -5
	s_cbranch_scc1 .Lscan_w1
	s_waitcnt vmcnt(42)
.Lscan_w1:
	s_waitcnt vmcnt(48)
	v_cvt_pk_bf16_f32 v206, v210, v211
	v_cvt_pk_bf16_f32 v207, v212, v213
	v_cvt_pk_bf16_f32 v208, v214, v215
	v_cvt_pk_bf16_f32 v209, v216, v217
	v_lshlrev_b32_e32 v212, 16, v94
	v_and_b32_e32 v213, 0xffff0000, v94
	v_lshlrev_b32_e32 v214, 16, v95
	v_and_b32_e32 v215, 0xffff0000, v95
	v_cvt_pk_bf16_f32 v210, v232, v233
	v_cvt_pk_bf16_f32 v211, v234, v235
	v_mfma_f32_16x16x32_bf16 v[74:77], v[74:77], v[206:209], v[212:215]
	v_lshlrev_b32_e32 v242, 16, v96
	v_and_b32_e32 v243, 0xffff0000, v96
	v_lshlrev_b32_e32 v244, 16, v97
	v_and_b32_e32 v245, 0xffff0000, v97
	v_lshlrev_b32_e32 v246, 16, v66
	v_and_b32_e32 v247, 0xffff0000, v66
	v_lshlrev_b32_e32 v248, 16, v67
	v_and_b32_e32 v249, 0xffff0000, v67
	v_lshlrev_b32_e32 v250, 16, v68
	v_and_b32_e32 v251, 0xffff0000, v68
	v_lshlrev_b32_e32 v252, 16, v69
	v_and_b32_e32 v253, 0xffff0000, v69
	v_cvt_pk_bf16_f32 v212, v202, v203
	v_cvt_pk_bf16_f32 v213, v204, v205
	s_nop 1
	v_mfma_f32_16x16x32_bf16 v[54:57], v[54:57], v[206:209], v[242:245]
	v_mfma_f32_16x16x32_bf16 v[46:49], v[46:49], v[206:209], v[246:249]
	v_mfma_f32_16x16x32_bf16 v[30:33], v[30:33], v[206:209], v[250:253]
	v_mfma_f32_16x16x32_bf16 v[202:205], v[70:73], v[210:213], v[74:77]
	v_mfma_f32_16x16x32_bf16 v[214:217], v[58:61], v[210:213], v[54:57]
	v_mfma_f32_16x16x32_bf16 v[232:235], v[42:45], v[210:213], v[46:49]
	v_add_co_u32_e32 v42, vcc, s11, v230
	s_nop 1
	v_addc_co_u32_e32 v43, vcc, -1, v231, vcc
	global_store_dwordx4 v[42:43], v[206:209], off offset:-64 nt
	global_store_dwordx4 v[42:43], v[210:213], off nt
	s_nop 0
	v_mfma_f32_16x16x32_bf16 v[206:209], v[26:29], v[210:213], v[30:33]
	s_add_i32 s0, s14, 11
	s_min_u32 s0, s0, s10
	s_lshl_b32 s0, s0, 13
	v_lshl_add_u64 v[26:27], v[226:227], 0, s[0:1]
	global_load_dwordx4 v[74:77], v[26:27], off
	global_load_dwordx4 v[70:73], v[26:27], off offset:64
	global_load_dwordx4 v[54:57], v[26:27], off offset:2048
	global_load_dwordx4 v[58:61], v[26:27], off offset:2112
	v_add_co_u32_e32 v26, vcc, s9, v26
	v_lshl_add_u64 v[66:67], v[228:229], 0, s[0:1]
	s_nop 0
	v_addc_co_u32_e32 v27, vcc, 0, v27, vcc
	global_load_dwordx4 v[46:49], v[26:27], off
	global_load_dwordx4 v[42:45], v[26:27], off offset:64
	global_load_dwordx4 v[30:33], v[26:27], off offset:2048
	s_nop 0
	global_load_dwordx4 v[26:29], v[26:27], off offset:2112
	s_nop 0
	global_load_dwordx4 v[94:97], v[66:67], off
	s_nop 0
	global_load_dwordx4 v[66:69], v[66:67], off offset:64
	s_cmp_lg_u32 s6, -5
	s_cbranch_scc1 .Lscan_w2
	s_waitcnt vmcnt(44)
; DI unsigned pack2(float lo, float hi) { f32x2_t v = {lo, hi}; bf16x2_t b = __builtin_convertvector(v, bf16x2_t); return __builtin_bit_cast(unsigned, b); }
; DI float bflo(unsigned u) { return __uint_as_float(u << 16); }
; DI float bfhi(unsigned u) { return __uint_as_float(u & 0xffff0000u); }
; #define PINM do { asm volatile("" ::: "memory"); __builtin_amdgcn_sched_barrier(0); } while (0)
; DI void scan_step(const ScanSlot& s, f32x4 (&acc)[4], u16* sst, int irow, int g) {
;     unsigned pk[4][2];
; #pragma unroll
;     for (int mt = 0; mt < 4; ++mt) { pk[mt][0] = pack2(acc[mt][0], acc[mt][1]); pk[mt][1] = pack2(acc[mt][2], acc[mt][3]); }
;     bf16x8 bfr[2];
; #pragma unroll
;     for (int ks = 0; ks < 2; ++ks) { uint4 w = {pk[2 * ks][0], pk[2 * ks][1], pk[2 * ks + 1][0], pk[2 * ks + 1][1]}; bfr[ks] = __builtin_bit_cast(bf16x8, w);
;         { typedef unsigned u32x4_ __attribute__((ext_vector_type(4))); const u32x4_ wv_ = {w.x, w.y, w.z, w.w}; __builtin_nontemporal_store(wv_, (u32x4_*)(sst + irow * 64 + 32 * ks + 8 * g)); } }
; #pragma unroll
;     for (int mt = 0; mt < 4; ++mt) {
;         const unsigned hx = (mt & 1) ? s.gh[mt >> 1].z : s.gh[mt >> 1].x, hy = (mt & 1) ? s.gh[mt >> 1].w : s.gh[mt >> 1].y;
;         f32x4 c = {bflo(hx), bfhi(hx), bflo(hy), bfhi(hy)};
; #pragma unroll
;         for (int ks = 0; ks < 2; ++ks) c = __builtin_amdgcn_mfma_f32_16x16x32_bf16(__builtin_bit_cast(bf16x8, s.ga[mt][ks]), bfr[ks], c, 0, 0, 0);
;         acc[mt] = c;
;     }
; DI void scan_item(const Params& p, int item, int lane) {
;     ...
;             scan_step(s2, acc, SST + (size_t)(u + 2) * 4096, irow, g); PINM; scan_load(s2, GT, HH, min(u + 7, ul), irow, i16, g); PINM;
;             scan_step(s3, acc, SST + (size_t)(u + 3) * 4096, irow, g); PINM; scan_load(s3, GT, HH, min(u + 8, ul), irow, i16, g); PINM;
.Lscan_w2:
	s_waitcnt vmcnt(48)
	v_cvt_pk_bf16_f32 v202, v202, v203
	v_cvt_pk_bf16_f32 v203, v204, v205
	v_cvt_pk_bf16_f32 v204, v214, v215
	v_cvt_pk_bf16_f32 v205, v216, v217
	v_lshlrev_b32_e32 v212, 16, v118
	v_and_b32_e32 v213, 0xffff0000, v118
	v_lshlrev_b32_e32 v214, 16, v119
	v_and_b32_e32 v215, 0xffff0000, v119
	v_cvt_pk_bf16_f32 v210, v232, v233
	v_cvt_pk_bf16_f32 v211, v234, v235
	v_mfma_f32_16x16x32_bf16 v[38:41], v[38:41], v[202:205], v[212:215]
	v_lshlrev_b32_e32 v242, 16, v120
	v_and_b32_e32 v243, 0xffff0000, v120
	v_lshlrev_b32_e32 v244, 16, v121
	v_and_b32_e32 v245, 0xffff0000, v121
	v_lshlrev_b32_e32 v246, 16, v114
	v_and_b32_e32 v247, 0xffff0000, v114
	v_lshlrev_b32_e32 v248, 16, v115
	v_and_b32_e32 v249, 0xffff0000, v115
	v_lshlrev_b32_e32 v250, 16, v116
	v_and_b32_e32 v251, 0xffff0000, v116
	v_lshlrev_b32_e32 v252, 16, v117
	v_and_b32_e32 v253, 0xffff0000, v117
	v_cvt_pk_bf16_f32 v212, v206, v207
	v_cvt_pk_bf16_f32 v213, v208, v209
	s_nop 1
	v_mfma_f32_16x16x32_bf16 v[22:25], v[22:25], v[202:205], v[242:245]
	v_mfma_f32_16x16x32_bf16 v[14:17], v[14:17], v[202:205], v[246:249]
	v_mfma_f32_16x16x32_bf16 v[6:9], v[6:9], v[202:205], v[250:253]
	v_mfma_f32_16x16x32_bf16 v[206:209], v[34:37], v[210:213], v[38:41]
	v_mfma_f32_16x16x32_bf16 v[214:217], v[18:21], v[210:213], v[22:25]
	v_mfma_f32_16x16x32_bf16 v[232:235], v[10:13], v[210:213], v[14:17]
	v_add_co_u32_e32 v10, vcc, s12, v230
	s_nop 1
	v_addc_co_u32_e32 v11, vcc, -1, v231, vcc
	global_store_dwordx4 v[10:11], v[202:205], off offset:-64 nt
	global_store_dwordx4 v[10:11], v[210:213], off nt
	s_nop 0
	v_mfma_f32_16x16x32_bf16 v[202:205], v[2:5], v[210:213], v[6:9]
	s_add_i32 s0, s14, 12
	s_min_u32 s0, s0, s10
	s_lshl_b32 s0, s0, 13
	v_lshl_add_u64 v[2:3], v[226:227], 0, s[0:1]
	global_load_dwordx4 v[38:41], v[2:3], off
	global_load_dwordx4 v[34:37], v[2:3], off offset:64
	global_load_dwordx4 v[22:25], v[2:3], off offset:2048
	global_load_dwordx4 v[18:21], v[2:3], off offset:2112
	v_add_co_u32_e32 v2, vcc, s9, v2
	v_lshl_add_u64 v[114:115], v[228:229], 0, s[0:1]
	s_nop 0
	v_addc_co_u32_e32 v3, vcc, 0, v3, vcc
	global_load_dwordx4 v[14:17], v[2:3], off
	global_load_dwordx4 v[10:13], v[2:3], off offset:64
	global_load_dwordx4 v[6:9], v[2:3], off offset:2048
	s_nop 0
	global_load_dwordx4 v[2:5], v[2:3], off offset:2112
	s_nop 0
	global_load_dwordx4 v[118:121], v[114:115], off
	s_nop 0
	global_load_dwordx4 v[114:117], v[114:115], off offset:64
	s_cmp_lg_u32 s6, -5
	s_cbranch_scc1 .Lscan_w3
	s_waitcnt vmcnt(46)
.Lscan_w3:
	s_waitcnt vmcnt(48)
	v_cvt_pk_bf16_f32 v206, v206, v207
	v_cvt_pk_bf16_f32 v207, v208, v209
	v_cvt_pk_bf16_f32 v208, v214, v215
	v_cvt_pk_bf16_f32 v209, v216, v217
	v_lshlrev_b32_e32 v212, 16, v194
	v_and_b32_e32 v213, 0xffff0000, v194
	v_lshlrev_b32_e32 v214, 16, v195
	v_and_b32_e32 v215, 0xffff0000, v195
	v_cvt_pk_bf16_f32 v210, v232, v233
	v_cvt_pk_bf16_f32 v211, v234, v235
	v_mfma_f32_16x16x32_bf16 v[178:181], v[178:181], v[206:209], v[212:215]
	v_lshlrev_b32_e32 v242, 16, v196
	v_and_b32_e32 v243, 0xffff0000, v196
	v_lshlrev_b32_e32 v244, 16, v197
	v_and_b32_e32 v245, 0xffff0000, v197
	v_lshlrev_b32_e32 v246, 16, v166
	v_and_b32_e32 v247, 0xffff0000, v166
	v_lshlrev_b32_e32 v248, 16, v167
	v_and_b32_e32 v249, 0xffff0000, v167
	v_lshlrev_b32_e32 v250, 16, v168
	v_and_b32_e32 v251, 0xffff0000, v168
	v_lshlrev_b32_e32 v252, 16, v169
	v_and_b32_e32 v253, 0xffff0000, v169
	v_cvt_pk_bf16_f32 v212, v202, v203
	v_cvt_pk_bf16_f32 v213, v204, v205
	s_nop 1
	v_mfma_f32_16x16x32_bf16 v[146:149], v[146:149], v[206:209], v[242:245]
	v_mfma_f32_16x16x32_bf16 v[130:133], v[130:133], v[206:209], v[246:249]
	v_mfma_f32_16x16x32_bf16 v[126:129], v[126:129], v[206:209], v[250:253]
	v_mfma_f32_16x16x32_bf16 v[202:205], v[162:165], v[210:213], v[178:181]
	v_mfma_f32_16x16x32_bf16 v[214:217], v[150:153], v[210:213], v[146:149]
	v_mfma_f32_16x16x32_bf16 v[232:235], v[138:141], v[210:213], v[130:133]
	v_add_co_u32_e32 v130, vcc, s13, v230
	s_nop 1
	v_addc_co_u32_e32 v131, vcc, -1, v231, vcc
	global_store_dwordx4 v[130:131], v[206:209], off offset:-64 nt
	global_store_dwordx4 v[130:131], v[210:213], off nt
	s_nop 0
	v_mfma_f32_16x16x32_bf16 v[206:209], v[122:125], v[210:213], v[126:129]
	s_add_i32 s0, s14, 13
	s_min_u32 s0, s0, s10
	s_lshl_b32 s0, s0, 13
	v_lshl_add_u64 v[122:123], v[226:227], 0, s[0:1]
	global_load_dwordx4 v[178:181], v[122:123], off
	global_load_dwordx4 v[162:165], v[122:123], off offset:64
	global_load_dwordx4 v[146:149], v[122:123], off offset:2048
	global_load_dwordx4 v[150:153], v[122:123], off offset:2112
	v_add_co_u32_e32 v122, vcc, s9, v122
	v_lshl_add_u64 v[166:167], v[228:229], 0, s[0:1]
	s_nop 0
	v_addc_co_u32_e32 v123, vcc, 0, v123, vcc
	global_load_dwordx4 v[130:133], v[122:123], off
	global_load_dwordx4 v[138:141], v[122:123], off offset:64
	global_load_dwordx4 v[126:129], v[122:123], off offset:2048
	s_nop 0
	global_load_dwordx4 v[122:125], v[122:123], off offset:2112
	s_nop 0
	global_load_dwordx4 v[194:197], v[166:167], off
	s_nop 0
	global_load_dwordx4 v[166:169], v[166:167], off offset:64
	s_waitcnt vmcnt(48)
; DI unsigned pack2(float lo, float hi) { f32x2_t v = {lo, hi}; bf16x2_t b = __builtin_convertvector(v, bf16x2_t); return __builtin_bit_cast(unsigned, b); }
; DI float bflo(unsigned u) { return __uint_as_float(u << 16); }
; DI float bfhi(unsigned u) { return __uint_as_float(u & 0xffff0000u); }
; #define PINM do { asm volatile("" ::: "memory"); __builtin_amdgcn_sched_barrier(0); } while (0)
; DI void scan_step(const ScanSlot& s, f32x4 (&acc)[4], u16* sst, int irow, int g) {
;     unsigned pk[4][2];
; #pragma unroll
;     for (int mt = 0; mt < 4; ++mt) { pk[mt][0] = pack2(acc[mt][0], acc[mt][1]); pk[mt][1] = pack2(acc[mt][2], acc[mt][3]); }
;     bf16x8 bfr[2];
; #pragma unroll
;     for (int ks = 0; ks < 2; ++ks) { uint4 w = {pk[2 * ks][0], pk[2 * ks][1], pk[2 * ks + 1][0], pk[2 * ks + 1][1]}; bfr[ks] = __builtin_bit_cast(bf16x8, w);
;         { typedef unsigned u32x4_ __attribute__((ext_vector_type(4))); const u32x4_ wv_ = {w.x, w.y, w.z, w.w}; __builtin_nontemporal_store(wv_, (u32x4_*)(sst + irow * 64 + 32 * ks + 8 * g)); } }
; #pragma unroll
;     for (int mt = 0; mt < 4; ++mt) {
;         const unsigned hx = (mt & 1) ? s.gh[mt >> 1].z : s.gh[mt >> 1].x, hy = (mt & 1) ? s.gh[mt >> 1].w : s.gh[mt >> 1].y;
;         f32x4 c = {bflo(hx), bfhi(hx), bflo(hy), bfhi(hy)};
; #pragma unroll
;         for (int ks = 0; ks < 2; ++ks) c = __builtin_amdgcn_mfma_f32_16x16x32_bf16(__builtin_bit_cast(bf16x8, s.ga[mt][ks]), bfr[ks], c, 0, 0, 0);
;         acc[mt] = c;
;     }
; DI void scan_item(const Params& p, int item, int lane) {
;     ...
;             scan_step(s4, acc, SST + (size_t)(u + 4) * 4096, irow, g); PINM; scan_load(s4, GT, HH, min(u + 9, ul), irow, i16, g); PINM;
;         }
	v_cvt_pk_bf16_f32 v210, v202, v203
	v_cvt_pk_bf16_f32 v211, v204, v205
	v_cvt_pk_bf16_f32 v212, v214, v215
	v_cvt_pk_bf16_f32 v213, v216, v217
	v_lshlrev_b32_e32 v202, 16, v198
	v_and_b32_e32 v203, 0xffff0000, v198
	v_lshlrev_b32_e32 v204, 16, v199
	v_and_b32_e32 v205, 0xffff0000, v199
	v_cvt_pk_bf16_f32 v232, v232, v233
	v_cvt_pk_bf16_f32 v233, v234, v235
	v_mfma_f32_16x16x32_bf16 v[190:193], v[190:193], v[210:213], v[202:205]
	v_lshlrev_b32_e32 v242, 16, v200
	v_and_b32_e32 v243, 0xffff0000, v200
	v_lshlrev_b32_e32 v244, 16, v201
	v_and_b32_e32 v245, 0xffff0000, v201
	v_lshlrev_b32_e32 v246, 16, v186
	v_and_b32_e32 v247, 0xffff0000, v186
	v_lshlrev_b32_e32 v248, 16, v187
	v_and_b32_e32 v249, 0xffff0000, v187
	v_lshlrev_b32_e32 v250, 16, v188
	v_and_b32_e32 v251, 0xffff0000, v188
	v_lshlrev_b32_e32 v252, 16, v189
	v_and_b32_e32 v253, 0xffff0000, v189
	v_cvt_pk_bf16_f32 v234, v206, v207
	v_cvt_pk_bf16_f32 v235, v208, v209
	global_store_dwordx4 v[230:231], v[210:213], off offset:-64 nt
	global_store_dwordx4 v[230:231], v[232:235], off nt
	s_nop 1
	v_mfma_f32_16x16x32_bf16 v[170:173], v[170:173], v[210:213], v[242:245]
	v_mfma_f32_16x16x32_bf16 v[154:157], v[154:157], v[210:213], v[246:249]
	v_mfma_f32_16x16x32_bf16 v[142:145], v[142:145], v[210:213], v[250:253]
	v_mfma_f32_16x16x32_bf16 v[206:209], v[182:185], v[232:235], v[190:193]
	v_mfma_f32_16x16x32_bf16 v[214:217], v[174:177], v[232:235], v[170:173]
	v_mfma_f32_16x16x32_bf16 v[202:205], v[158:161], v[232:235], v[154:157]
	v_mfma_f32_16x16x32_bf16 v[210:213], v[134:137], v[232:235], v[142:145]
	s_add_i32 s14, s14, 14
	s_min_u32 s0, s14, s10
	s_lshl_b32 s0, s0, 13
	v_lshl_add_u64 v[134:135], v[226:227], 0, s[0:1]
	global_load_dwordx4 v[190:193], v[134:135], off
	global_load_dwordx4 v[182:185], v[134:135], off offset:64
	global_load_dwordx4 v[170:173], v[134:135], off offset:2048
	global_load_dwordx4 v[174:177], v[134:135], off offset:2112
	v_add_co_u32_e32 v134, vcc, s9, v134
	v_lshl_add_u64 v[186:187], v[228:229], 0, s[0:1]
	s_nop 0
	v_addc_co_u32_e32 v135, vcc, 0, v135, vcc
	global_load_dwordx4 v[154:157], v[134:135], off
	global_load_dwordx4 v[158:161], v[134:135], off offset:64
	global_load_dwordx4 v[142:145], v[134:135], off offset:2048
	s_nop 0
	global_load_dwordx4 v[134:137], v[134:135], off offset:2112
	s_nop 0
	global_load_dwordx4 v[198:201], v[186:187], off
	s_nop 0
	global_load_dwordx4 v[186:189], v[186:187], off offset:64
	s_add_i32 s6, s6, 5
	s_cmpk_gt_u32 s6, 0x77
	v_lshl_add_u64 v[230:231], v[230:231], 0, s[4:5]
	s_cbranch_scc0 .LBB0_438
; DI unsigned pack2(float lo, float hi) { f32x2_t v = {lo, hi}; bf16x2_t b = __builtin_convertvector(v, bf16x2_t); return __builtin_bit_cast(unsigned, b); }
; DI float bflo(unsigned u) { return __uint_as_float(u << 16); }
; DI float bfhi(unsigned u) { return __uint_as_float(u & 0xffff0000u); }
; #define PINM do { asm volatile("" ::: "memory"); __builtin_amdgcn_sched_barrier(0); } while (0)
; DI void scan_step(const ScanSlot& s, f32x4 (&acc)[4], u16* sst, int irow, int g) {
;     unsigned pk[4][2];
; #pragma unroll
;     for (int mt = 0; mt < 4; ++mt) { pk[mt][0] = pack2(acc[mt][0], acc[mt][1]); pk[mt][1] = pack2(acc[mt][2], acc[mt][3]); }
;     bf16x8 bfr[2];
; #pragma unroll
;     for (int ks = 0; ks < 2; ++ks) { uint4 w = {pk[2 * ks][0], pk[2 * ks][1], pk[2 * ks + 1][0], pk[2 * ks + 1][1]}; bfr[ks] = __builtin_bit_cast(bf16x8, w);
;         { typedef unsigned u32x4_ __attribute__((ext_vector_type(4))); const u32x4_ wv_ = {w.x, w.y, w.z, w.w}; __builtin_nontemporal_store(wv_, (u32x4_*)(sst + irow * 64 + 32 * ks + 8 * g)); } }
; #pragma unroll
;     for (int mt = 0; mt < 4; ++mt) {
;         const unsigned hx = (mt & 1) ? s.gh[mt >> 1].z : s.gh[mt >> 1].x, hy = (mt & 1) ? s.gh[mt >> 1].w : s.gh[mt >> 1].y;
;         f32x4 c = {bflo(hx), bfhi(hx), bflo(hy), bfhi(hy)};
; #pragma unroll
;         for (int ks = 0; ks < 2; ++ks) c = __builtin_amdgcn_mfma_f32_16x16x32_bf16(__builtin_bit_cast(bf16x8, s.ga[mt][ks]), bfr[ks], c, 0, 0, 0);
;         acc[mt] = c;
;     }
; DI void scan_item(const Params& p, int item, int lane) {
;     ...
;         scan_step(s0, acc, SST + (size_t)(u0 + 125) * 4096, irow, g); PINM;
;         scan_step(s1, acc, SST + (size_t)(u0 + 126) * 4096, irow, g); PINM;
;         scan_step(s2, acc, SST + (size_t)(u0 + 127) * 4096, irow, g);
;     ...
;         float* fout = p.out + O_SP + (size_t)bh * 4096;
; #pragma unroll
;         for (int mt = 0; mt < 4; ++mt) *(f32x4*)(fout + irow * 64 + 16 * mt + 4 * g) = acc[mt];
	s_waitcnt vmcnt(0)
	v_cvt_pk_bf16_f32 v122, v206, v207
	v_cvt_pk_bf16_f32 v123, v208, v209
	v_cvt_pk_bf16_f32 v124, v214, v215
	v_cvt_pk_bf16_f32 v125, v216, v217
	v_lshlrev_b32_e32 v130, 16, v110
	v_and_b32_e32 v131, 0xffff0000, v110
	v_lshlrev_b32_e32 v132, 16, v111
	v_and_b32_e32 v133, 0xffff0000, v111
	v_cvt_pk_bf16_f32 v126, v202, v203
	v_cvt_pk_bf16_f32 v127, v204, v205
	v_mfma_f32_16x16x32_bf16 v[106:109], v[106:109], v[122:125], v[130:133]
	v_cvt_pk_bf16_f32 v128, v210, v211
	v_cvt_pk_bf16_f32 v129, v212, v213
	s_add_u32 s0, s54, 0xea14800
	s_addc_u32 s1, s55, 0
	v_mfma_f32_16x16x32_bf16 v[102:105], v[102:105], v[126:129], v[106:109]
	s_add_u32 s4, s0, s3
	s_addc_u32 s5, s1, 0
	v_lshlrev_b32_e32 v110, 1, v222
	v_lshlrev_b32_e32 v106, 16, v112
	v_and_b32_e32 v107, 0xffff0000, v112
	v_lshlrev_b32_e32 v108, 16, v113
	v_and_b32_e32 v109, 0xffff0000, v113
	v_mov_b32_e32 v111, 0
	v_lshlrev_b32_e32 v130, 1, v224
	v_mfma_f32_16x16x32_bf16 v[90:93], v[90:93], v[122:125], v[106:109]
	v_mov_b32_e32 v131, v111
	s_mov_b32 s3, 0xfa000
	v_mfma_f32_16x16x32_bf16 v[86:89], v[86:89], v[126:129], v[90:93]
	v_lshl_add_u64 v[106:107], s[4:5], 0, v[110:111]
	v_lshl_add_u64 v[106:107], v[106:107], 0, v[130:131]
	s_mov_b64 s[4:5], 0xfa000
	s_nop 1
	v_lshlrev_b32_e32 v90, 16, v98
	v_and_b32_e32 v91, 0xffff0000, v98
	v_lshlrev_b32_e32 v92, 16, v99
	v_and_b32_e32 v93, 0xffff0000, v99
	s_nop 1
	v_mfma_f32_16x16x32_bf16 v[82:85], v[82:85], v[122:125], v[90:93]
	v_mfma_f32_16x16x32_bf16 v[78:81], v[78:81], v[126:129], v[82:85]
	s_nop 1
	v_lshl_add_u64 v[90:91], v[106:107], 0, s[4:5]
	s_nop 3
	v_lshlrev_b32_e32 v82, 16, v100
	v_and_b32_e32 v83, 0xffff0000, v100
	v_lshlrev_b32_e32 v84, 16, v101
	v_and_b32_e32 v85, 0xffff0000, v101
	s_nop 1
	v_mfma_f32_16x16x32_bf16 v[62:65], v[62:65], v[122:125], v[82:85]
	s_nop 2
	v_add_co_u32_e32 v82, vcc, s3, v106
	v_mfma_f32_16x16x32_bf16 v[50:53], v[50:53], v[126:129], v[62:65]
	s_nop 0
	v_addc_co_u32_e32 v83, vcc, 0, v107, vcc
	global_store_dwordx4 v[82:83], v[122:125], off nt
	global_store_dwordx4 v[90:91], v[126:129], off offset:64 nt
	v_cvt_pk_bf16_f32 v62, v102, v103
	v_cvt_pk_bf16_f32 v63, v104, v105
	v_cvt_pk_bf16_f32 v64, v86, v87
	v_cvt_pk_bf16_f32 v65, v88, v89
	v_lshlrev_b32_e32 v82, 16, v94
	v_and_b32_e32 v83, 0xffff0000, v94
	v_lshlrev_b32_e32 v84, 16, v95
	v_and_b32_e32 v85, 0xffff0000, v95
	v_cvt_pk_bf16_f32 v78, v78, v79
	v_cvt_pk_bf16_f32 v79, v80, v81
	v_mfma_f32_16x16x32_bf16 v[74:77], v[74:77], v[62:65], v[82:85]
	v_cvt_pk_bf16_f32 v80, v50, v51
	v_cvt_pk_bf16_f32 v81, v52, v53
	s_mov_b32 s3, 0xfc000
	s_mov_b64 s[4:5], 0xfc000
	v_mfma_f32_16x16x32_bf16 v[50:53], v[70:73], v[78:81], v[74:77]
	v_lshlrev_b32_e32 v70, 16, v96
	v_and_b32_e32 v71, 0xffff0000, v96
	v_lshlrev_b32_e32 v72, 16, v97
	v_and_b32_e32 v73, 0xffff0000, v97
	s_nop 1
	v_mfma_f32_16x16x32_bf16 v[54:57], v[54:57], v[62:65], v[70:73]
	v_mfma_f32_16x16x32_bf16 v[54:57], v[58:61], v[78:81], v[54:57]
	v_lshlrev_b32_e32 v58, 16, v66
	v_and_b32_e32 v59, 0xffff0000, v66
	v_lshlrev_b32_e32 v60, 16, v67
	v_and_b32_e32 v61, 0xffff0000, v67
	s_nop 1
	v_mfma_f32_16x16x32_bf16 v[46:49], v[46:49], v[62:65], v[58:61]
	v_mfma_f32_16x16x32_bf16 v[42:45], v[42:45], v[78:81], v[46:49]
	s_nop 1
	v_lshl_add_u64 v[58:59], v[106:107], 0, s[4:5]
	s_nop 3
	v_lshlrev_b32_e32 v46, 16, v68
	v_and_b32_e32 v47, 0xffff0000, v68
	v_lshlrev_b32_e32 v48, 16, v69
	v_and_b32_e32 v49, 0xffff0000, v69
	s_nop 1
	v_mfma_f32_16x16x32_bf16 v[30:33], v[30:33], v[62:65], v[46:49]
	s_nop 2
	v_add_co_u32_e32 v46, vcc, s3, v106
	v_mfma_f32_16x16x32_bf16 v[26:29], v[26:29], v[78:81], v[30:33]
	s_nop 0
	v_addc_co_u32_e32 v47, vcc, 0, v107, vcc
	global_store_dwordx4 v[46:47], v[62:65], off nt
	global_store_dwordx4 v[58:59], v[78:81], off offset:64 nt
	v_cvt_pk_bf16_f32 v30, v50, v51
	v_cvt_pk_bf16_f32 v31, v52, v53
	v_cvt_pk_bf16_f32 v32, v54, v55
	v_cvt_pk_bf16_f32 v33, v56, v57
	v_lshlrev_b32_e32 v46, 16, v118
	v_and_b32_e32 v47, 0xffff0000, v118
	v_lshlrev_b32_e32 v48, 16, v119
	v_and_b32_e32 v49, 0xffff0000, v119
	v_cvt_pk_bf16_f32 v42, v42, v43
	v_cvt_pk_bf16_f32 v43, v44, v45
	v_mfma_f32_16x16x32_bf16 v[38:41], v[38:41], v[30:33], v[46:49]
	v_cvt_pk_bf16_f32 v44, v26, v27
	v_cvt_pk_bf16_f32 v45, v28, v29
	s_lshl_b32 s3, s10, 13
	s_add_u32 s0, s0, s3
	v_mfma_f32_16x16x32_bf16 v[26:29], v[34:37], v[42:45], v[38:41]
	v_lshlrev_b32_e32 v34, 16, v120
	v_and_b32_e32 v35, 0xffff0000, v120
	v_lshlrev_b32_e32 v36, 16, v121
	v_and_b32_e32 v37, 0xffff0000, v121
	s_addc_u32 s1, s1, 0
	s_nop 0
	v_mfma_f32_16x16x32_bf16 v[22:25], v[22:25], v[30:33], v[34:37]
	v_mfma_f32_16x16x32_bf16 v[18:21], v[18:21], v[42:45], v[22:25]
	s_nop 6
	v_lshlrev_b32_e32 v22, 16, v114
	v_and_b32_e32 v23, 0xffff0000, v114
	v_lshlrev_b32_e32 v24, 16, v115
	v_and_b32_e32 v25, 0xffff0000, v115
	s_nop 1
	v_mfma_f32_16x16x32_bf16 v[14:17], v[14:17], v[30:33], v[22:25]
	v_mfma_f32_16x16x32_bf16 v[10:13], v[10:13], v[42:45], v[14:17]
	s_nop 1
	v_lshl_add_u64 v[22:23], s[0:1], 0, v[110:111]
	s_lshl_b32 s0, s2, 12
	s_add_u32 s0, s52, s0
	s_nop 1
	v_lshlrev_b32_e32 v14, 16, v116
	v_and_b32_e32 v15, 0xffff0000, v116
	v_lshlrev_b32_e32 v16, 16, v117
	v_and_b32_e32 v17, 0xffff0000, v117
	s_addc_u32 s1, s53, 0
	v_lshlrev_b32_e32 v110, 2, v222
	v_mfma_f32_16x16x32_bf16 v[6:9], v[6:9], v[30:33], v[14:17]
	v_mfma_f32_16x16x32_bf16 v[2:5], v[2:5], v[42:45], v[6:9]
	s_nop 1
	v_lshl_add_u64 v[14:15], v[22:23], 0, v[130:131]
	global_store_dwordx4 v[14:15], v[30:33], off nt
	global_store_dwordx4 v[14:15], v[42:45], off offset:64 nt
	s_nop 1
	v_lshl_add_u64 v[6:7], s[0:1], 0, v[110:111]
	v_lshlrev_b32_e32 v110, 4, v225
	v_lshl_add_u64 v[6:7], v[6:7], 0, v[110:111]
	s_mov_b64 s[0:1], 0x4800000
	v_lshl_add_u64 v[8:9], v[6:7], 0, s[0:1]
	v_add_co_u32_e32 v6, vcc, 0x4800000, v6
	s_nop 1
	v_addc_co_u32_e32 v7, vcc, 0, v7, vcc
	global_store_dwordx4 v[6:7], v[26:29], off
	global_store_dwordx4 v[8:9], v[18:21], off offset:64
	global_store_dwordx4 v[8:9], v[10:13], off offset:128
	global_store_dwordx4 v[8:9], v[2:5], off offset:192
	s_branch .LBB0_440
